# mode-0 K-loop load segments made VALU-free: LDS-DMA in saddr form (SGPR base + 32-bit lane offset), B-fragment base precomputed per tile with immediate buffer offsets; on top of v037
# speedup vs baseline: 1.0221x; 1.0221x over previous
; #define PG8_STAGE(bufoff, gbase, voff) do { _Pragma("unroll") for (int _i = 0; _i < 2; ++_i) \
;         __builtin_amdgcn_global_load_lds((const unsigned*)((const char*)(gbase) + (voff)[_i]), (LAS unsigned*)(lds + (bufoff) + ldsw + _i * 8192), 16, 0, 0); } while (0)
; #define PG8_LDA(dst, b, h) do { _Pragma("unroll") for (int m = 0; m < 4; ++m) _Pragma("unroll") for (int k = 0; k < 2; ++k) dst[m][k] = *(const LAS bf16x8*)(lds + PG8_SA(b, h) + aoff + m * 2048 + k * 1024); } while (0)
; #define PG8_LDB(dst, b, h) do { _Pragma("unroll") for (int n = 0; n < 2; ++n) _Pragma("unroll") for (int k = 0; k < 2; ++k) dst[n][k] = *(const LAS bf16x8*)(lds + PG8_SB(b, h) + boff + n * 2048 + k * 1024); } while (0)
; #define PG8_MMA(ai, bj, At, Bt) do { __builtin_amdgcn_s_setprio(1); _Pragma("unroll") for (int m = 0; m < 4; ++m) _Pragma("unroll") for (int n = 0; n < 2; ++n) _Pragma("unroll") for (int k = 0; k < 2; ++k) \
;         acc[ai][bj][m][n] = __builtin_amdgcn_mfma_f32_16x16x32_bf16(Bt[n][k], At[m][k], acc[ai][bj][m][n], 0, 0, 0); __builtin_amdgcn_s_setprio(0); } while (0)
; #define PG8_WAIT_L(n) asm volatile("s_waitcnt lgkmcnt(" #n ")" ::: "memory")
; #define PG8_BAR __builtin_amdgcn_s_barrier()
; #define PG8_SCHED __builtin_amdgcn_sched_barrier(0)
; template <int MODE, class EpiT, class Sched>
; __device__ __forceinline__ void gemm_phase(LAS unsigned char* lds, const Gemm g, const Sched& S, const EpiT& E) {
;     ...
;         for (int t = 0; t < nt; t += 2) {
;             const bool last = (t == nt - 2);
;             const char* a1 = cA + (size_t)(t + 1) * kstep;
;             const char* a2 = last ? nA : cA + (size_t)(t + 2) * kstep; const char* b2 = last ? nB : cB + (size_t)(t + 2) * kstep;
;             const char* a3 = a2 + kstep; const char* b3 = b2 + kstep;
;             PG8_LDB(B0, 0, 0); PG8_SCHED; PG8_LDA(At, 0, 0); PG8_STAGE(PG8_SA(1, 1), a1 + hstep, voffA);
;             PG8_WAIT_L(8); PG8_BAR; PG8_WAIT_L(0); PG8_MMA(0, 0, At, B0); PG8_BAR; PG8_SCHED;
;             PG8_LDB(B1, 0, 1); PG8_STAGE(PG8_SB(0, 0), b2, voffB);
;             PG8_BAR; PG8_WAIT_L(0); PG8_MMA(0, 1, At, B1); PG8_BAR;
;             PG8_LDA(At, 0, 1); PG8_STAGE(PG8_SA(0, 0), a2, voffA);
;             PG8_BAR; PG8_WAIT_L(0); PG8_MMA(1, 0, At, B0); PG8_BAR; PG8_SCHED;
.LBB0_331:
	s_mov_b32 s22, 0
	s_mov_b64 s[4:5], 0x100
	s_add_u32 s100, s12, s21
	s_addc_u32 s101, s13, 0
	s_add_u32 s100, s100, 0x80
	s_addc_u32 s101, s101, 0
	v_add_u32_e32 v145, 0x10000, v141
.LBB0_332:
	s_add_i32 s23, s22, 2
	s_add_u32 s30, s12, s4
	s_addc_u32 s38, s13, s5
	s_add_u32 s44, s10, s4
	s_addc_u32 s45, s11, s5
	s_add_i32 s58, 0, 0x10000
	ds_read_b128 v[146:149], v145
	ds_read_b128 v[150:153], v145 offset:1024
	ds_read_b128 v[154:157], v145 offset:2048
	ds_read_b128 v[158:161], v145 offset:3072
	s_cmp_eq_u32 s55, s22
	s_cselect_b32 s39, s29, s38
	s_cselect_b32 s38, s28, s30
	s_cselect_b32 s45, s35, s45
	s_cselect_b32 s44, s34, s44
	s_add_i32 m0, s47, 0xc000
	ds_read_b128 v[162:165], v144
	ds_read_b128 v[166:169], v144 offset:1024
	ds_read_b128 v[170:173], v144 offset:2048
	ds_read_b128 v[174:177], v144 offset:3072
	ds_read_b128 v[182:185], v144 offset:4096
	ds_read_b128 v[186:189], v144 offset:5120
	ds_read_b128 v[190:193], v144 offset:6144
	ds_read_b128 v[194:197], v144 offset:7168
	global_load_lds_dwordx4 v0, s[100:101]
	s_add_i32 m0, s47, 0xe000
	s_nop 0
	global_load_lds_dwordx4 v130, s[100:101]
	s_waitcnt lgkmcnt(8)
	s_barrier
	s_waitcnt lgkmcnt(0)
	v_mfma_f32_16x16x32_bf16 v[126:129], v[146:149], v[162:165], v[126:129]
	v_mfma_f32_16x16x32_bf16 v[122:125], v[154:157], v[162:165], v[122:125]
	v_mfma_f32_16x16x32_bf16 v[118:121], v[146:149], v[170:173], v[118:121]
	v_mfma_f32_16x16x32_bf16 v[114:117], v[154:157], v[170:173], v[114:117]
	v_mfma_f32_16x16x32_bf16 v[110:113], v[146:149], v[182:185], v[110:113]
	v_mfma_f32_16x16x32_bf16 v[106:109], v[154:157], v[182:185], v[106:109]
	v_mfma_f32_16x16x32_bf16 v[102:105], v[146:149], v[190:193], v[102:105]
	v_mfma_f32_16x16x32_bf16 v[98:101], v[154:157], v[190:193], v[98:101]
	v_mfma_f32_16x16x32_bf16 v[126:129], v[150:153], v[166:169], v[126:129]
	v_mfma_f32_16x16x32_bf16 v[122:125], v[158:161], v[166:169], v[122:125]
	v_mfma_f32_16x16x32_bf16 v[118:121], v[150:153], v[174:177], v[118:121]
	v_mfma_f32_16x16x32_bf16 v[114:117], v[158:161], v[174:177], v[114:117]
	v_mfma_f32_16x16x32_bf16 v[110:113], v[150:153], v[186:189], v[110:113]
	v_mfma_f32_16x16x32_bf16 v[106:109], v[158:161], v[186:189], v[106:109]
	v_mfma_f32_16x16x32_bf16 v[102:105], v[150:153], v[194:197], v[102:105]
	v_mfma_f32_16x16x32_bf16 v[98:101], v[158:161], v[194:197], v[98:101]
	s_barrier
	s_add_i32 s22, 0, 0x14000
	s_add_i32 s30, s58, s46
	s_add_u32 s98, s44, 0x80
	s_addc_u32 s99, s45, 0
	s_mov_b32 m0, s30
	ds_read_b128 v[220:223], v145 offset:16384
	ds_read_b128 v[224:227], v145 offset:17408
	ds_read_b128 v[228:231], v145 offset:18432
	ds_read_b128 v[232:235], v145 offset:19456
	global_load_lds_dwordx4 v0, s[44:45]
	s_add_i32 m0, s30, 0x2000
	s_nop 0
	global_load_lds_dwordx4 v130, s[44:45]
	s_barrier
	s_waitcnt lgkmcnt(0)
	v_mfma_f32_16x16x32_bf16 v[94:97], v[220:223], v[162:165], v[94:97]
	v_mfma_f32_16x16x32_bf16 v[90:93], v[228:231], v[162:165], v[90:93]
	v_mfma_f32_16x16x32_bf16 v[86:89], v[220:223], v[170:173], v[86:89]
	v_mfma_f32_16x16x32_bf16 v[82:85], v[228:231], v[170:173], v[82:85]
	v_mfma_f32_16x16x32_bf16 v[78:81], v[220:223], v[182:185], v[78:81]
	v_mfma_f32_16x16x32_bf16 v[74:77], v[228:231], v[182:185], v[74:77]
	v_mfma_f32_16x16x32_bf16 v[70:73], v[220:223], v[190:193], v[70:73]
	v_mfma_f32_16x16x32_bf16 v[66:69], v[228:231], v[190:193], v[66:69]
	v_mfma_f32_16x16x32_bf16 v[94:97], v[224:227], v[166:169], v[94:97]
	v_mfma_f32_16x16x32_bf16 v[90:93], v[232:235], v[166:169], v[90:93]
	v_mfma_f32_16x16x32_bf16 v[86:89], v[224:227], v[174:177], v[86:89]
	v_mfma_f32_16x16x32_bf16 v[82:85], v[232:235], v[174:177], v[82:85]
	v_mfma_f32_16x16x32_bf16 v[78:81], v[224:227], v[186:189], v[78:81]
	v_mfma_f32_16x16x32_bf16 v[74:77], v[232:235], v[186:189], v[74:77]
	v_mfma_f32_16x16x32_bf16 v[70:73], v[224:227], v[194:197], v[70:73]
	v_mfma_f32_16x16x32_bf16 v[66:69], v[232:235], v[194:197], v[66:69]
	s_barrier
	s_mov_b32 m0, s47
	ds_read_b128 v[162:165], v144 offset:16384
	ds_read_b128 v[166:169], v144 offset:17408
	ds_read_b128 v[170:173], v144 offset:18432
	ds_read_b128 v[174:177], v144 offset:19456
	ds_read_b128 v[182:185], v144 offset:20480
	ds_read_b128 v[186:189], v144 offset:21504
	ds_read_b128 v[190:193], v144 offset:22528
	ds_read_b128 v[194:197], v144 offset:23552
	global_load_lds_dwordx4 v0, s[38:39]
	s_mov_b32 m0, s50
	s_nop 0
	global_load_lds_dwordx4 v130, s[38:39]
	s_barrier
	s_waitcnt lgkmcnt(0)
	v_mfma_f32_16x16x32_bf16 v[62:65], v[146:149], v[162:165], v[62:65]
	v_mfma_f32_16x16x32_bf16 v[58:61], v[154:157], v[162:165], v[58:61]
	v_mfma_f32_16x16x32_bf16 v[54:57], v[146:149], v[170:173], v[54:57]
	v_mfma_f32_16x16x32_bf16 v[50:53], v[154:157], v[170:173], v[50:53]
	v_mfma_f32_16x16x32_bf16 v[46:49], v[146:149], v[182:185], v[46:49]
	v_mfma_f32_16x16x32_bf16 v[42:45], v[154:157], v[182:185], v[42:45]
	v_mfma_f32_16x16x32_bf16 v[38:41], v[146:149], v[190:193], v[38:41]
	v_mfma_f32_16x16x32_bf16 v[34:37], v[154:157], v[190:193], v[34:37]
	v_mfma_f32_16x16x32_bf16 v[62:65], v[150:153], v[166:169], v[62:65]
	v_mfma_f32_16x16x32_bf16 v[58:61], v[158:161], v[166:169], v[58:61]
	v_mfma_f32_16x16x32_bf16 v[54:57], v[150:153], v[174:177], v[54:57]
	v_mfma_f32_16x16x32_bf16 v[50:53], v[158:161], v[174:177], v[50:53]
	v_mfma_f32_16x16x32_bf16 v[46:49], v[150:153], v[186:189], v[46:49]
	v_mfma_f32_16x16x32_bf16 v[42:45], v[158:161], v[186:189], v[42:45]
	v_mfma_f32_16x16x32_bf16 v[38:41], v[150:153], v[194:197], v[38:41]
	v_mfma_f32_16x16x32_bf16 v[34:37], v[158:161], v[194:197], v[34:37]
	s_barrier
; #define PG8_STAGE(bufoff, gbase, voff) do { _Pragma("unroll") for (int _i = 0; _i < 2; ++_i) \
;         __builtin_amdgcn_global_load_lds((const unsigned*)((const char*)(gbase) + (voff)[_i]), (LAS unsigned*)(lds + (bufoff) + ldsw + _i * 8192), 16, 0, 0); } while (0)
; #define PG8_LDA(dst, b, h) do { _Pragma("unroll") for (int m = 0; m < 4; ++m) _Pragma("unroll") for (int k = 0; k < 2; ++k) dst[m][k] = *(const LAS bf16x8*)(lds + PG8_SA(b, h) + aoff + m * 2048 + k * 1024); } while (0)
; #define PG8_LDB(dst, b, h) do { _Pragma("unroll") for (int n = 0; n < 2; ++n) _Pragma("unroll") for (int k = 0; k < 2; ++k) dst[n][k] = *(const LAS bf16x8*)(lds + PG8_SB(b, h) + boff + n * 2048 + k * 1024); } while (0)
; #define PG8_MMA(ai, bj, At, Bt) do { __builtin_amdgcn_s_setprio(1); _Pragma("unroll") for (int m = 0; m < 4; ++m) _Pragma("unroll") for (int n = 0; n < 2; ++n) _Pragma("unroll") for (int k = 0; k < 2; ++k) \
;         acc[ai][bj][m][n] = __builtin_amdgcn_mfma_f32_16x16x32_bf16(Bt[n][k], At[m][k], acc[ai][bj][m][n], 0, 0, 0); __builtin_amdgcn_s_setprio(0); } while (0)
; #define PG8_WAIT_V(n) asm volatile("s_waitcnt vmcnt(" #n ")" ::: "memory")
; #define PG8_WAIT_L(n) asm volatile("s_waitcnt lgkmcnt(" #n ")" ::: "memory")
; #define PG8_BAR __builtin_amdgcn_s_barrier()
; #define PG8_SCHED __builtin_amdgcn_sched_barrier(0)
; template <int MODE, class EpiT, class Sched>
; __device__ __forceinline__ void gemm_phase(LAS unsigned char* lds, const Gemm g, const Sched& S, const EpiT& E) {
;     ...
;             PG8_STAGE(PG8_SB(0, 1), b2 + hstep, voffB);
;             PG8_WAIT_V(6); PG8_BAR; PG8_MMA(1, 1, At, B1); PG8_BAR;
;             PG8_LDB(B0, 1, 0); PG8_SCHED; PG8_LDA(At, 1, 0); PG8_STAGE(PG8_SA(0, 1), a2 + hstep, voffA);
;             PG8_WAIT_L(8); PG8_BAR; PG8_WAIT_L(0); PG8_MMA(0, 0, At, B0); PG8_BAR; PG8_SCHED;
;             PG8_LDB(B1, 1, 1); PG8_STAGE(PG8_SB(1, 0), b3, voffB);
;             PG8_BAR; PG8_WAIT_L(0); PG8_MMA(0, 1, At, B1); PG8_BAR;
;             PG8_LDA(At, 1, 1); PG8_STAGE(PG8_SA(1, 0), a3, voffA);
	s_add_u32 s44, s44, s21
	s_addc_u32 s45, s45, 0
	s_add_i32 s22, s22, s46
	s_mov_b32 m0, s22
	s_nop 0
	global_load_lds_dwordx4 v0, s[44:45]
	s_add_i32 m0, s22, 0x2000
	s_nop 0
	global_load_lds_dwordx4 v130, s[44:45]
	s_waitcnt vmcnt(6)
	s_barrier
	v_mfma_f32_16x16x32_bf16 v[30:33], v[220:223], v[162:165], v[30:33]
	v_mfma_f32_16x16x32_bf16 v[26:29], v[228:231], v[162:165], v[26:29]
	v_mfma_f32_16x16x32_bf16 v[22:25], v[220:223], v[170:173], v[22:25]
	v_mfma_f32_16x16x32_bf16 v[18:21], v[228:231], v[170:173], v[18:21]
	v_mfma_f32_16x16x32_bf16 v[14:17], v[220:223], v[182:185], v[14:17]
	v_mfma_f32_16x16x32_bf16 v[10:13], v[228:231], v[182:185], v[10:13]
	v_mfma_f32_16x16x32_bf16 v[6:9], v[220:223], v[190:193], v[6:9]
	v_mfma_f32_16x16x32_bf16 v[2:5], v[228:231], v[190:193], v[2:5]
	v_mfma_f32_16x16x32_bf16 v[30:33], v[224:227], v[166:169], v[30:33]
	v_mfma_f32_16x16x32_bf16 v[26:29], v[232:235], v[166:169], v[26:29]
	v_mfma_f32_16x16x32_bf16 v[22:25], v[224:227], v[174:177], v[22:25]
	v_mfma_f32_16x16x32_bf16 v[18:21], v[232:235], v[174:177], v[18:21]
	v_mfma_f32_16x16x32_bf16 v[14:17], v[224:227], v[186:189], v[14:17]
	v_mfma_f32_16x16x32_bf16 v[10:13], v[232:235], v[186:189], v[10:13]
	v_mfma_f32_16x16x32_bf16 v[6:9], v[224:227], v[194:197], v[6:9]
	v_mfma_f32_16x16x32_bf16 v[2:5], v[232:235], v[194:197], v[2:5]
	s_barrier
	s_add_i32 s22, 0, 0x18000
	ds_read_b128 v[146:149], v145 offset:32768
	ds_read_b128 v[150:153], v145 offset:33792
	ds_read_b128 v[154:157], v145 offset:34816
	ds_read_b128 v[158:161], v145 offset:35840
	s_add_u32 s38, s38, s21
	s_addc_u32 s39, s39, 0
	s_mov_b32 m0, s51
	ds_read_b128 v[162:165], v144 offset:32768
	ds_read_b128 v[166:169], v144 offset:33792
	ds_read_b128 v[170:173], v144 offset:34816
	ds_read_b128 v[174:177], v144 offset:35840
	ds_read_b128 v[182:185], v144 offset:36864
	ds_read_b128 v[186:189], v144 offset:37888
	ds_read_b128 v[190:193], v144 offset:38912
	ds_read_b128 v[194:197], v144 offset:39936
	global_load_lds_dwordx4 v0, s[38:39]
	s_mov_b32 m0, s52
	s_nop 0
	global_load_lds_dwordx4 v130, s[38:39]
	s_waitcnt lgkmcnt(8)
	s_barrier
	s_waitcnt lgkmcnt(0)
	v_mfma_f32_16x16x32_bf16 v[126:129], v[146:149], v[162:165], v[126:129]
	v_mfma_f32_16x16x32_bf16 v[122:125], v[154:157], v[162:165], v[122:125]
	v_mfma_f32_16x16x32_bf16 v[118:121], v[146:149], v[170:173], v[118:121]
	v_mfma_f32_16x16x32_bf16 v[114:117], v[154:157], v[170:173], v[114:117]
	v_mfma_f32_16x16x32_bf16 v[110:113], v[146:149], v[182:185], v[110:113]
	v_mfma_f32_16x16x32_bf16 v[106:109], v[154:157], v[182:185], v[106:109]
	v_mfma_f32_16x16x32_bf16 v[102:105], v[146:149], v[190:193], v[102:105]
	v_mfma_f32_16x16x32_bf16 v[98:101], v[154:157], v[190:193], v[98:101]
	v_mfma_f32_16x16x32_bf16 v[126:129], v[150:153], v[166:169], v[126:129]
	v_mfma_f32_16x16x32_bf16 v[122:125], v[158:161], v[166:169], v[122:125]
	v_mfma_f32_16x16x32_bf16 v[118:121], v[150:153], v[174:177], v[118:121]
	v_mfma_f32_16x16x32_bf16 v[114:117], v[158:161], v[174:177], v[114:117]
	v_mfma_f32_16x16x32_bf16 v[110:113], v[150:153], v[186:189], v[110:113]
	v_mfma_f32_16x16x32_bf16 v[106:109], v[158:161], v[186:189], v[106:109]
	v_mfma_f32_16x16x32_bf16 v[102:105], v[150:153], v[194:197], v[102:105]
	v_mfma_f32_16x16x32_bf16 v[98:101], v[158:161], v[194:197], v[98:101]
	s_barrier
	s_add_i32 s30, 0, 0x1c000
	s_add_i32 s22, s22, s46
	s_mov_b32 m0, s22
	ds_read_b128 v[220:223], v145 offset:49152
	ds_read_b128 v[224:227], v145 offset:50176
	ds_read_b128 v[228:231], v145 offset:51200
	ds_read_b128 v[232:235], v145 offset:52224
	global_load_lds_dwordx4 v0, s[98:99]
	s_add_i32 m0, s22, 0x2000
	s_nop 0
	global_load_lds_dwordx4 v130, s[98:99]
	s_barrier
	s_waitcnt lgkmcnt(0)
	v_mfma_f32_16x16x32_bf16 v[94:97], v[220:223], v[162:165], v[94:97]
	v_mfma_f32_16x16x32_bf16 v[90:93], v[228:231], v[162:165], v[90:93]
	v_mfma_f32_16x16x32_bf16 v[86:89], v[220:223], v[170:173], v[86:89]
	v_mfma_f32_16x16x32_bf16 v[82:85], v[228:231], v[170:173], v[82:85]
	v_mfma_f32_16x16x32_bf16 v[78:81], v[220:223], v[182:185], v[78:81]
	v_mfma_f32_16x16x32_bf16 v[74:77], v[228:231], v[182:185], v[74:77]
	v_mfma_f32_16x16x32_bf16 v[70:73], v[220:223], v[190:193], v[70:73]
	v_mfma_f32_16x16x32_bf16 v[66:69], v[228:231], v[190:193], v[66:69]
	v_mfma_f32_16x16x32_bf16 v[94:97], v[224:227], v[166:169], v[94:97]
	v_mfma_f32_16x16x32_bf16 v[90:93], v[232:235], v[166:169], v[90:93]
	v_mfma_f32_16x16x32_bf16 v[86:89], v[224:227], v[174:177], v[86:89]
	v_mfma_f32_16x16x32_bf16 v[82:85], v[232:235], v[174:177], v[82:85]
	v_mfma_f32_16x16x32_bf16 v[78:81], v[224:227], v[186:189], v[78:81]
	v_mfma_f32_16x16x32_bf16 v[74:77], v[232:235], v[186:189], v[74:77]
	v_mfma_f32_16x16x32_bf16 v[70:73], v[224:227], v[194:197], v[70:73]
	v_mfma_f32_16x16x32_bf16 v[66:69], v[232:235], v[194:197], v[66:69]
	s_barrier
	s_mov_b32 m0, s53
	s_sub_u32 s98, s38, s21
	s_subb_u32 s99, s39, 0
	s_add_u32 s98, s98, 0x80
	s_addc_u32 s99, s99, 0
	ds_read_b128 v[162:165], v144 offset:49152
	ds_read_b128 v[166:169], v144 offset:50176
	ds_read_b128 v[170:173], v144 offset:51200
	ds_read_b128 v[174:177], v144 offset:52224
	ds_read_b128 v[182:185], v144 offset:53248
	ds_read_b128 v[186:189], v144 offset:54272
	ds_read_b128 v[190:193], v144 offset:55296
	ds_read_b128 v[194:197], v144 offset:56320
	global_load_lds_dwordx4 v0, s[98:99]
	s_mov_b32 m0, s54
	s_nop 0
	global_load_lds_dwordx4 v130, s[98:99]
	s_barrier
; __device__ __forceinline__ unsigned pk2(float lo, float hi) { unsigned r; asm volatile("v_cvt_pk_bf16_f32 %0, %1, %2" : "=v"(r) : "v"(lo), "v"(hi)); return r; }
; __device__ __forceinline__ float siluf_(float x) { return x * __builtin_amdgcn_rcpf(1.0f + __expf(-x)); }
; #define PG8_STAGE(bufoff, gbase, voff) do { _Pragma("unroll") for (int _i = 0; _i < 2; ++_i) \
;         __builtin_amdgcn_global_load_lds((const unsigned*)((const char*)(gbase) + (voff)[_i]), (LAS unsigned*)(lds + (bufoff) + ldsw + _i * 8192), 16, 0, 0); } while (0)
; #define PG8_MMA(ai, bj, At, Bt) do { __builtin_amdgcn_s_setprio(1); _Pragma("unroll") for (int m = 0; m < 4; ++m) _Pragma("unroll") for (int n = 0; n < 2; ++n) _Pragma("unroll") for (int k = 0; k < 2; ++k) \
;         acc[ai][bj][m][n] = __builtin_amdgcn_mfma_f32_16x16x32_bf16(Bt[n][k], At[m][k], acc[ai][bj][m][n], 0, 0, 0); __builtin_amdgcn_s_setprio(0); } while (0)
; #define PG8_BAR __builtin_amdgcn_s_barrier()
;     template <int mode> __device__ __forceinline__ void run(const f32x4 (&acc)[2][2][4][2], const Unit& u, int wr, int wc, int fr, int fq, const LAS float* sc) const {
;     ...
;         if (mode == 0) {
;             const int col0 = u.pn * HALF + wc * 32 + 8 * fq;
; #pragma unroll
;             for (int ai = 0; ai < 2; ++ai)
; #pragma unroll
;                 for (int m = 0; m < 4; ++m) {
;                     const int row = row0 + ai * HALF + m * 16;
;                     const float s = sc[ai * HALF + wr * 64 + m * 16 + fr];
;                     const f32x4 g0 = acc[ai][0][m][0] * s, u0 = acc[ai][1][m][0] * s, g1 = acc[ai][0][m][1] * s, u1 = acc[ai][1][m][1] * s;
;                     u32x4 w;
;                     w.x = pk2(siluf_(g0[0]) * u0[0], siluf_(g0[1]) * u0[1]); w.y = pk2(siluf_(g0[2]) * u0[2], siluf_(g0[3]) * u0[3]);
;                     w.z = pk2(siluf_(g1[0]) * u1[0], siluf_(g1[1]) * u1[1]); w.w = pk2(siluf_(g1[2]) * u1[2], siluf_(g1[3]) * u1[3]);
;                     *(u32x4*)(ob + (size_t)row * FF + col0) = w;
; template <int MODE, class EpiT, class Sched>
; __device__ __forceinline__ void gemm_phase(LAS unsigned char* lds, const Gemm g, const Sched& S, const EpiT& E) {
;     ...
;             PG8_BAR; PG8_WAIT_L(0); PG8_MMA(1, 0, At, B0); PG8_BAR; PG8_SCHED;
;             PG8_STAGE(PG8_SB(1, 1), b3 + hstep, voffB);
;             PG8_WAIT_V(6); PG8_BAR; PG8_MMA(1, 1, At, B1); PG8_BAR;
;         }
	s_waitcnt lgkmcnt(0)
	v_mfma_f32_16x16x32_bf16 v[62:65], v[146:149], v[162:165], v[62:65]
	v_mfma_f32_16x16x32_bf16 v[58:61], v[154:157], v[162:165], v[58:61]
	v_mfma_f32_16x16x32_bf16 v[54:57], v[146:149], v[170:173], v[54:57]
	v_mfma_f32_16x16x32_bf16 v[50:53], v[154:157], v[170:173], v[50:53]
	v_mfma_f32_16x16x32_bf16 v[46:49], v[146:149], v[182:185], v[46:49]
	v_mfma_f32_16x16x32_bf16 v[42:45], v[154:157], v[182:185], v[42:45]
	v_mfma_f32_16x16x32_bf16 v[38:41], v[146:149], v[190:193], v[38:41]
	v_mfma_f32_16x16x32_bf16 v[34:37], v[154:157], v[190:193], v[34:37]
	v_mfma_f32_16x16x32_bf16 v[62:65], v[150:153], v[166:169], v[62:65]
	v_mfma_f32_16x16x32_bf16 v[58:61], v[158:161], v[166:169], v[58:61]
	v_mfma_f32_16x16x32_bf16 v[54:57], v[150:153], v[174:177], v[54:57]
	v_mfma_f32_16x16x32_bf16 v[50:53], v[158:161], v[174:177], v[50:53]
	v_mfma_f32_16x16x32_bf16 v[46:49], v[150:153], v[186:189], v[46:49]
	v_mfma_f32_16x16x32_bf16 v[42:45], v[158:161], v[186:189], v[42:45]
	v_mfma_f32_16x16x32_bf16 v[38:41], v[150:153], v[194:197], v[38:41]
	v_mfma_f32_16x16x32_bf16 v[34:37], v[158:161], v[194:197], v[34:37]
	s_barrier
	s_add_i32 s22, s30, s46
	s_add_u32 s98, s44, 0x80
	s_addc_u32 s99, s45, 0
	s_mov_b32 m0, s22
	s_nop 0
	global_load_lds_dwordx4 v0, s[98:99]
	s_add_i32 m0, s22, 0x2000
	s_nop 0
	global_load_lds_dwordx4 v130, s[98:99]
	s_waitcnt vmcnt(6)
	s_barrier
	v_mfma_f32_16x16x32_bf16 v[30:33], v[220:223], v[162:165], v[30:33]
	v_mfma_f32_16x16x32_bf16 v[26:29], v[228:231], v[162:165], v[26:29]
	v_mfma_f32_16x16x32_bf16 v[22:25], v[220:223], v[170:173], v[22:25]
	v_mfma_f32_16x16x32_bf16 v[18:21], v[228:231], v[170:173], v[18:21]
	v_mfma_f32_16x16x32_bf16 v[14:17], v[220:223], v[182:185], v[14:17]
	v_mfma_f32_16x16x32_bf16 v[10:13], v[228:231], v[182:185], v[10:13]
	v_mfma_f32_16x16x32_bf16 v[6:9], v[220:223], v[190:193], v[6:9]
	v_mfma_f32_16x16x32_bf16 v[2:5], v[228:231], v[190:193], v[2:5]
	v_mfma_f32_16x16x32_bf16 v[30:33], v[224:227], v[166:169], v[30:33]
	v_mfma_f32_16x16x32_bf16 v[26:29], v[232:235], v[166:169], v[26:29]
	v_mfma_f32_16x16x32_bf16 v[22:25], v[224:227], v[174:177], v[22:25]
	v_mfma_f32_16x16x32_bf16 v[18:21], v[232:235], v[174:177], v[18:21]
	v_mfma_f32_16x16x32_bf16 v[14:17], v[224:227], v[186:189], v[14:17]
	v_mfma_f32_16x16x32_bf16 v[10:13], v[232:235], v[186:189], v[10:13]
	v_mfma_f32_16x16x32_bf16 v[6:9], v[224:227], v[194:197], v[6:9]
	v_mfma_f32_16x16x32_bf16 v[2:5], v[232:235], v[194:197], v[2:5]
	s_barrier
	s_add_u32 s4, s4, 0x100
	s_addc_u32 s5, s5, 0
	s_add_u32 s100, s100, 0x100
	s_addc_u32 s101, s101, 0
	s_cmp_ge_u32 s23, s16
	s_mov_b32 s22, s23
	s_cbranch_scc0 .LBB0_332
	v_lshl_add_u32 v145, s57, 10, v142
	ds_read_b32 v136, v145
	v_lshl_or_b32 v138, s8, 7, v143
	v_lshl_add_u32 v146, s9, 8, v140
	v_ashrrev_i32_e32 v139, 31, v138
	v_lshlrev_b64 v[138:139], 1, v[138:139]
	s_waitcnt lgkmcnt(0)
	v_pk_mul_f32 v[148:149], v[126:127], v[136:137] op_sel_hi:[1,0]
	v_pk_mul_f32 v[154:155], v[94:95], v[136:137] op_sel_hi:[1,0]
	v_mul_f32_e32 v147, 0xbfb8aa3b, v148
	v_exp_f32_e32 v147, v147
	v_pk_mul_f32 v[150:151], v[128:129], v[136:137] op_sel_hi:[1,0]
	v_pk_mul_f32 v[152:153], v[96:97], v[136:137] op_sel_hi:[1,0]
	v_pk_mul_f32 v[158:159], v[122:123], v[136:137] op_sel_hi:[1,0]
	v_add_f32_e32 v147, 1.0, v147
	v_rcp_f32_e32 v147, v147
	v_pk_mul_f32 v[156:157], v[124:125], v[136:137] op_sel_hi:[1,0]
	v_pk_mul_f32 v[160:161], v[92:93], v[136:137] op_sel_hi:[1,0]
	v_pk_mul_f32 v[136:137], v[90:91], v[136:137] op_sel_hi:[1,0]
	v_mul_f32_e32 v147, v148, v147
	v_mul_f32_e32 v148, 0xbfb8aa3b, v149
	v_exp_f32_e32 v148, v148
	v_mul_f32_e32 v147, v154, v147
	s_and_b64 vcc, exec, s[42:43]
	v_add_f32_e32 v148, 1.0, v148
	v_rcp_f32_e32 v148, v148
	s_nop 0
	v_mul_f32_e32 v148, v149, v148
	v_mul_f32_e32 v148, v155, v148
	v_cvt_pk_bf16_f32 v148, v147, v148
	v_mul_f32_e32 v147, 0xbfb8aa3b, v150
	v_mul_f32_e32 v149, 0xbfb8aa3b, v151
	v_exp_f32_e32 v147, v147
	v_exp_f32_e32 v149, v149
	v_add_f32_e32 v147, 1.0, v147
	v_add_f32_e32 v149, 1.0, v149
	v_rcp_f32_e32 v147, v147
	v_rcp_f32_e32 v149, v149
	v_mul_f32_e32 v147, v150, v147
	v_mul_f32_e32 v149, v151, v149
	v_mul_f32_e32 v147, v152, v147
	v_mul_f32_e32 v149, v153, v149
	v_cvt_pk_bf16_f32 v149, v147, v149
	v_mul_f32_e32 v147, 0xbfb8aa3b, v158
	v_exp_f32_e32 v147, v147
	s_nop 0
	v_add_f32_e32 v147, 1.0, v147
	v_rcp_f32_e32 v147, v147
	s_nop 0
	v_mul_f32_e32 v147, v158, v147
	v_mul_f32_e32 v136, v136, v147
	v_mul_f32_e32 v147, 0xbfb8aa3b, v159
	v_exp_f32_e32 v147, v147
	s_nop 0
	v_add_f32_e32 v147, 1.0, v147
	v_rcp_f32_e32 v147, v147
	s_nop 0
	v_mul_f32_e32 v147, v159, v147
	v_mul_f32_e32 v137, v137, v147
	v_cvt_pk_bf16_f32 v150, v136, v137
	v_mul_f32_e32 v136, 0xbfb8aa3b, v156
	v_mul_f32_e32 v137, 0xbfb8aa3b, v157
	v_exp_f32_e32 v136, v136
	v_exp_f32_e32 v137, v137
	v_or_b32_e32 v147, 16, v146
	v_add_f32_e32 v136, 1.0, v136
	v_add_f32_e32 v137, 1.0, v137
	v_rcp_f32_e32 v136, v136
	v_rcp_f32_e32 v137, v137
	v_mul_f32_e32 v136, v156, v136
	v_mul_f32_e32 v137, v157, v137
	v_mul_f32_e32 v136, v160, v136
	v_mul_f32_e32 v137, v161, v137
	v_cvt_pk_bf16_f32 v151, v136, v137
	v_mov_b64_e32 v[136:137], s[6:7]
	v_mad_i64_i32 v[152:153], s[4:5], v146, s33, v[136:137]
	v_lshl_add_u64 v[152:153], v[152:153], 0, v[138:139]
	global_store_dwordx4 v[152:153], v[148:151], off
	ds_read_b32 v148, v145 offset:64
	s_waitcnt lgkmcnt(0)
; __device__ __forceinline__ unsigned pk2(float lo, float hi) { unsigned r; asm volatile("v_cvt_pk_bf16_f32 %0, %1, %2" : "=v"(r) : "v"(lo), "v"(hi)); return r; }
; __device__ __forceinline__ float siluf_(float x) { return x * __builtin_amdgcn_rcpf(1.0f + __expf(-x)); }
;     template <int mode> __device__ __forceinline__ void run(const f32x4 (&acc)[2][2][4][2], const Unit& u, int wr, int wc, int fr, int fq, const LAS float* sc) const {
;     ...
;                     const int row = row0 + ai * HALF + m * 16;
;                     const float s = sc[ai * HALF + wr * 64 + m * 16 + fr];
;                     const f32x4 g0 = acc[ai][0][m][0] * s, u0 = acc[ai][1][m][0] * s, g1 = acc[ai][0][m][1] * s, u1 = acc[ai][1][m][1] * s;
;                     u32x4 w;
;                     w.x = pk2(siluf_(g0[0]) * u0[0], siluf_(g0[1]) * u0[1]); w.y = pk2(siluf_(g0[2]) * u0[2], siluf_(g0[3]) * u0[3]);
;                     w.z = pk2(siluf_(g1[0]) * u1[0], siluf_(g1[1]) * u1[1]); w.w = pk2(siluf_(g1[2]) * u1[2], siluf_(g1[3]) * u1[3]);
;                     *(u32x4*)(ob + (size_t)row * FF + col0) = w;
	v_pk_mul_f32 v[152:153], v[118:119], v[148:149] op_sel_hi:[1,0]
	v_pk_mul_f32 v[150:151], v[120:121], v[148:149] op_sel_hi:[1,0]
	v_pk_mul_f32 v[154:155], v[88:89], v[148:149] op_sel_hi:[1,0]
	v_pk_mul_f32 v[156:157], v[86:87], v[148:149] op_sel_hi:[1,0]
	v_pk_mul_f32 v[158:159], v[116:117], v[148:149] op_sel_hi:[1,0]
	v_pk_mul_f32 v[160:161], v[114:115], v[148:149] op_sel_hi:[1,0]
	v_pk_mul_f32 v[162:163], v[84:85], v[148:149] op_sel_hi:[1,0]
	v_pk_mul_f32 v[164:165], v[82:83], v[148:149] op_sel_hi:[1,0]
	v_mul_f32_e32 v148, 0xbfb8aa3b, v152
	v_mul_f32_e32 v149, 0xbfb8aa3b, v153
	v_exp_f32_e32 v148, v148
	v_exp_f32_e32 v149, v149
	v_add_f32_e32 v148, 1.0, v148
	v_add_f32_e32 v149, 1.0, v149
	v_rcp_f32_e32 v148, v148
	v_rcp_f32_e32 v149, v149
	v_mul_f32_e32 v148, v152, v148
	v_mul_f32_e32 v149, v153, v149
	v_mul_f32_e32 v148, v156, v148
	v_mul_f32_e32 v149, v157, v149
	v_cvt_pk_bf16_f32 v148, v148, v149
	v_mul_f32_e32 v149, 0xbfb8aa3b, v150
	v_exp_f32_e32 v149, v149
	v_mul_f32_e32 v152, 0xbfb8aa3b, v159
	v_exp_f32_e32 v152, v152
	v_add_f32_e32 v149, 1.0, v149
	v_rcp_f32_e32 v149, v149
	v_add_f32_e32 v152, 1.0, v152
	v_rcp_f32_e32 v152, v152
	v_mul_f32_e32 v149, v150, v149
	v_mul_f32_e32 v150, 0xbfb8aa3b, v151
	v_exp_f32_e32 v150, v150
	v_mul_f32_e32 v149, v154, v149
	v_mul_f32_e32 v152, v159, v152
	v_mul_f32_e32 v152, v163, v152
	v_add_f32_e32 v150, 1.0, v150
	v_rcp_f32_e32 v150, v150
	s_nop 0
	v_mul_f32_e32 v150, v151, v150
	v_mul_f32_e32 v150, v155, v150
	v_cvt_pk_bf16_f32 v149, v149, v150
	v_mul_f32_e32 v150, 0xbfb8aa3b, v160
	v_mul_f32_e32 v151, 0xbfb8aa3b, v161
	v_exp_f32_e32 v150, v150
	v_exp_f32_e32 v151, v151
	v_add_f32_e32 v150, 1.0, v150
	v_add_f32_e32 v151, 1.0, v151
	v_rcp_f32_e32 v150, v150
	v_rcp_f32_e32 v151, v151
	v_mul_f32_e32 v150, v160, v150
	v_mul_f32_e32 v151, v161, v151
	v_mul_f32_e32 v150, v164, v150
	v_mul_f32_e32 v151, v165, v151
	v_cvt_pk_bf16_f32 v150, v150, v151
	v_mul_f32_e32 v151, 0xbfb8aa3b, v158
	v_exp_f32_e32 v151, v151
	s_nop 0
	v_add_f32_e32 v151, 1.0, v151
	v_rcp_f32_e32 v151, v151
	s_nop 0
	v_mul_f32_e32 v151, v158, v151
	v_mul_f32_e32 v151, v162, v151
	v_cvt_pk_bf16_f32 v151, v151, v152
	v_mad_i64_i32 v[152:153], s[4:5], v147, s33, v[136:137]
	v_lshl_add_u64 v[152:153], v[152:153], 0, v[138:139]
	global_store_dwordx4 v[152:153], v[148:151], off
	ds_read_b32 v148, v145 offset:128
	v_or_b32_e32 v147, 32, v146
	s_waitcnt lgkmcnt(0)
	v_pk_mul_f32 v[152:153], v[110:111], v[148:149] op_sel_hi:[1,0]
	v_pk_mul_f32 v[150:151], v[112:113], v[148:149] op_sel_hi:[1,0]
	v_pk_mul_f32 v[154:155], v[80:81], v[148:149] op_sel_hi:[1,0]
	v_pk_mul_f32 v[156:157], v[78:79], v[148:149] op_sel_hi:[1,0]
	v_pk_mul_f32 v[158:159], v[108:109], v[148:149] op_sel_hi:[1,0]
	v_pk_mul_f32 v[160:161], v[106:107], v[148:149] op_sel_hi:[1,0]
	v_pk_mul_f32 v[162:163], v[76:77], v[148:149] op_sel_hi:[1,0]
	v_pk_mul_f32 v[164:165], v[74:75], v[148:149] op_sel_hi:[1,0]
	v_mul_f32_e32 v148, 0xbfb8aa3b, v152
	v_mul_f32_e32 v149, 0xbfb8aa3b, v153
	v_exp_f32_e32 v148, v148
	v_exp_f32_e32 v149, v149
	v_add_f32_e32 v148, 1.0, v148
	v_add_f32_e32 v149, 1.0, v149
	v_rcp_f32_e32 v148, v148
	v_rcp_f32_e32 v149, v149
	v_mul_f32_e32 v148, v152, v148
	v_mul_f32_e32 v149, v153, v149
	v_mul_f32_e32 v148, v156, v148
	v_mul_f32_e32 v149, v157, v149
	v_cvt_pk_bf16_f32 v148, v148, v149
	v_mul_f32_e32 v149, 0xbfb8aa3b, v150
	v_exp_f32_e32 v149, v149
	v_mul_f32_e32 v152, 0xbfb8aa3b, v159
	v_exp_f32_e32 v152, v152
	v_add_f32_e32 v149, 1.0, v149
	v_rcp_f32_e32 v149, v149
	v_add_f32_e32 v152, 1.0, v152
	v_rcp_f32_e32 v152, v152
	v_mul_f32_e32 v149, v150, v149
	v_mul_f32_e32 v150, 0xbfb8aa3b, v151
	v_exp_f32_e32 v150, v150
	v_mul_f32_e32 v149, v154, v149
	v_mul_f32_e32 v152, v159, v152
	v_mul_f32_e32 v152, v163, v152
	v_add_f32_e32 v150, 1.0, v150
	v_rcp_f32_e32 v150, v150
	s_nop 0
	v_mul_f32_e32 v150, v151, v150
	v_mul_f32_e32 v150, v155, v150
	v_cvt_pk_bf16_f32 v149, v149, v150
	v_mul_f32_e32 v150, 0xbfb8aa3b, v160
	v_mul_f32_e32 v151, 0xbfb8aa3b, v161
	v_exp_f32_e32 v150, v150
	v_exp_f32_e32 v151, v151
	v_add_f32_e32 v150, 1.0, v150
	v_add_f32_e32 v151, 1.0, v151
	v_rcp_f32_e32 v150, v150
	v_rcp_f32_e32 v151, v151
	v_mul_f32_e32 v150, v160, v150
	v_mul_f32_e32 v151, v161, v151
	v_mul_f32_e32 v150, v164, v150
	v_mul_f32_e32 v151, v165, v151
	v_cvt_pk_bf16_f32 v150, v150, v151
	v_mul_f32_e32 v151, 0xbfb8aa3b, v158
	v_exp_f32_e32 v151, v151
	s_nop 0
	v_add_f32_e32 v151, 1.0, v151
	v_rcp_f32_e32 v151, v151
	s_nop 0
	v_mul_f32_e32 v151, v158, v151
	v_mul_f32_e32 v151, v162, v151
	v_cvt_pk_bf16_f32 v151, v151, v152
	v_mad_i64_i32 v[152:153], s[4:5], v147, s33, v[136:137]
	v_lshl_add_u64 v[152:153], v[152:153], 0, v[138:139]
	global_store_dwordx4 v[152:153], v[148:151], off
	ds_read_b32 v148, v145 offset:192
	v_or_b32_e32 v147, 48, v146
	s_waitcnt lgkmcnt(0)
; __device__ __forceinline__ unsigned pk2(float lo, float hi) { unsigned r; asm volatile("v_cvt_pk_bf16_f32 %0, %1, %2" : "=v"(r) : "v"(lo), "v"(hi)); return r; }
; __device__ __forceinline__ float siluf_(float x) { return x * __builtin_amdgcn_rcpf(1.0f + __expf(-x)); }
;     template <int mode> __device__ __forceinline__ void run(const f32x4 (&acc)[2][2][4][2], const Unit& u, int wr, int wc, int fr, int fq, const LAS float* sc) const {
;     ...
;                     const int row = row0 + ai * HALF + m * 16;
;                     const float s = sc[ai * HALF + wr * 64 + m * 16 + fr];
;                     const f32x4 g0 = acc[ai][0][m][0] * s, u0 = acc[ai][1][m][0] * s, g1 = acc[ai][0][m][1] * s, u1 = acc[ai][1][m][1] * s;
;                     u32x4 w;
;                     w.x = pk2(siluf_(g0[0]) * u0[0], siluf_(g0[1]) * u0[1]); w.y = pk2(siluf_(g0[2]) * u0[2], siluf_(g0[3]) * u0[3]);
;                     w.z = pk2(siluf_(g1[0]) * u1[0], siluf_(g1[1]) * u1[1]); w.w = pk2(siluf_(g1[2]) * u1[2], siluf_(g1[3]) * u1[3]);
;                     *(u32x4*)(ob + (size_t)row * FF + col0) = w;
	v_pk_mul_f32 v[152:153], v[102:103], v[148:149] op_sel_hi:[1,0]
	v_pk_mul_f32 v[150:151], v[104:105], v[148:149] op_sel_hi:[1,0]
	v_pk_mul_f32 v[154:155], v[72:73], v[148:149] op_sel_hi:[1,0]
	v_pk_mul_f32 v[156:157], v[70:71], v[148:149] op_sel_hi:[1,0]
	v_pk_mul_f32 v[158:159], v[100:101], v[148:149] op_sel_hi:[1,0]
	v_pk_mul_f32 v[160:161], v[98:99], v[148:149] op_sel_hi:[1,0]
	v_pk_mul_f32 v[162:163], v[68:69], v[148:149] op_sel_hi:[1,0]
	v_pk_mul_f32 v[164:165], v[66:67], v[148:149] op_sel_hi:[1,0]
	v_mul_f32_e32 v148, 0xbfb8aa3b, v152
	v_mul_f32_e32 v149, 0xbfb8aa3b, v153
	v_exp_f32_e32 v148, v148
	v_exp_f32_e32 v149, v149
	v_add_f32_e32 v148, 1.0, v148
	v_add_f32_e32 v149, 1.0, v149
	v_rcp_f32_e32 v148, v148
	v_rcp_f32_e32 v149, v149
	v_mul_f32_e32 v148, v152, v148
	v_mul_f32_e32 v149, v153, v149
	v_mul_f32_e32 v148, v156, v148
	v_mul_f32_e32 v149, v157, v149
	v_cvt_pk_bf16_f32 v148, v148, v149
	v_mul_f32_e32 v149, 0xbfb8aa3b, v150
	v_exp_f32_e32 v149, v149
	v_mul_f32_e32 v152, 0xbfb8aa3b, v159
	v_exp_f32_e32 v152, v152
	v_add_f32_e32 v149, 1.0, v149
	v_rcp_f32_e32 v149, v149
	v_add_f32_e32 v152, 1.0, v152
	v_rcp_f32_e32 v152, v152
	v_mul_f32_e32 v149, v150, v149
	v_mul_f32_e32 v150, 0xbfb8aa3b, v151
	v_exp_f32_e32 v150, v150
	v_mul_f32_e32 v149, v154, v149
	v_mul_f32_e32 v152, v159, v152
	v_mul_f32_e32 v152, v163, v152
	v_add_f32_e32 v150, 1.0, v150
	v_rcp_f32_e32 v150, v150
	s_nop 0
	v_mul_f32_e32 v150, v151, v150
	v_mul_f32_e32 v150, v155, v150
	v_cvt_pk_bf16_f32 v149, v149, v150
	v_mul_f32_e32 v150, 0xbfb8aa3b, v160
	v_mul_f32_e32 v151, 0xbfb8aa3b, v161
	v_exp_f32_e32 v150, v150
	v_exp_f32_e32 v151, v151
	v_add_f32_e32 v150, 1.0, v150
	v_add_f32_e32 v151, 1.0, v151
	v_rcp_f32_e32 v150, v150
	v_rcp_f32_e32 v151, v151
	v_mul_f32_e32 v150, v160, v150
	v_mul_f32_e32 v151, v161, v151
	v_mul_f32_e32 v150, v164, v150
	v_mul_f32_e32 v151, v165, v151
	v_cvt_pk_bf16_f32 v150, v150, v151
	v_mul_f32_e32 v151, 0xbfb8aa3b, v158
	v_exp_f32_e32 v151, v151
	s_nop 0
	v_add_f32_e32 v151, 1.0, v151
	v_rcp_f32_e32 v151, v151
	s_nop 0
	v_mul_f32_e32 v151, v158, v151
	v_mul_f32_e32 v151, v162, v151
	v_cvt_pk_bf16_f32 v151, v151, v152
	v_mad_i64_i32 v[152:153], s[4:5], v147, s33, v[136:137]
	v_lshl_add_u64 v[152:153], v[152:153], 0, v[138:139]
	global_store_dwordx4 v[152:153], v[148:151], off
	ds_read_b32 v148, v145 offset:512
	v_add_u32_e32 v147, 0x80, v146
	s_waitcnt lgkmcnt(0)
	v_pk_mul_f32 v[152:153], v[62:63], v[148:149] op_sel_hi:[1,0]
	v_pk_mul_f32 v[150:151], v[64:65], v[148:149] op_sel_hi:[1,0]
	v_pk_mul_f32 v[154:155], v[32:33], v[148:149] op_sel_hi:[1,0]
	v_pk_mul_f32 v[156:157], v[30:31], v[148:149] op_sel_hi:[1,0]
	v_pk_mul_f32 v[158:159], v[60:61], v[148:149] op_sel_hi:[1,0]
	v_pk_mul_f32 v[160:161], v[58:59], v[148:149] op_sel_hi:[1,0]
	v_pk_mul_f32 v[162:163], v[28:29], v[148:149] op_sel_hi:[1,0]
	v_pk_mul_f32 v[164:165], v[26:27], v[148:149] op_sel_hi:[1,0]
	v_mul_f32_e32 v148, 0xbfb8aa3b, v152
	v_mul_f32_e32 v149, 0xbfb8aa3b, v153
	v_exp_f32_e32 v148, v148
	v_exp_f32_e32 v149, v149
	v_add_f32_e32 v148, 1.0, v148
	v_add_f32_e32 v149, 1.0, v149
	v_rcp_f32_e32 v148, v148
	v_rcp_f32_e32 v149, v149
	v_mul_f32_e32 v148, v152, v148
	v_mul_f32_e32 v149, v153, v149
	v_mul_f32_e32 v148, v156, v148
	v_mul_f32_e32 v149, v157, v149
	v_cvt_pk_bf16_f32 v148, v148, v149
	v_mul_f32_e32 v149, 0xbfb8aa3b, v150
	v_exp_f32_e32 v149, v149
	v_mul_f32_e32 v152, 0xbfb8aa3b, v159
	v_exp_f32_e32 v152, v152
	v_add_f32_e32 v149, 1.0, v149
	v_rcp_f32_e32 v149, v149
	v_add_f32_e32 v152, 1.0, v152
	v_rcp_f32_e32 v152, v152
	v_mul_f32_e32 v149, v150, v149
	v_mul_f32_e32 v150, 0xbfb8aa3b, v151
	v_exp_f32_e32 v150, v150
	v_mul_f32_e32 v149, v154, v149
	v_mul_f32_e32 v152, v159, v152
	v_mul_f32_e32 v152, v163, v152
	v_add_f32_e32 v150, 1.0, v150
	v_rcp_f32_e32 v150, v150
	s_nop 0
	v_mul_f32_e32 v150, v151, v150
	v_mul_f32_e32 v150, v155, v150
	v_cvt_pk_bf16_f32 v149, v149, v150
	v_mul_f32_e32 v150, 0xbfb8aa3b, v160
	v_mul_f32_e32 v151, 0xbfb8aa3b, v161
	v_exp_f32_e32 v150, v150
	v_exp_f32_e32 v151, v151
	v_add_f32_e32 v150, 1.0, v150
	v_add_f32_e32 v151, 1.0, v151
	v_rcp_f32_e32 v150, v150
	v_rcp_f32_e32 v151, v151
	v_mul_f32_e32 v150, v160, v150
	v_mul_f32_e32 v151, v161, v151
	v_mul_f32_e32 v150, v164, v150
	v_mul_f32_e32 v151, v165, v151
	v_cvt_pk_bf16_f32 v150, v150, v151
	v_mul_f32_e32 v151, 0xbfb8aa3b, v158
	v_exp_f32_e32 v151, v151
	s_nop 0
	v_add_f32_e32 v151, 1.0, v151
	v_rcp_f32_e32 v151, v151
	s_nop 0
	v_mul_f32_e32 v151, v158, v151
	v_mul_f32_e32 v151, v162, v151
	v_cvt_pk_bf16_f32 v151, v151, v152
	v_mad_i64_i32 v[152:153], s[4:5], v147, s33, v[136:137]
	v_lshl_add_u64 v[152:153], v[152:153], 0, v[138:139]
	global_store_dwordx4 v[152:153], v[148:151], off
	ds_read_b32 v148, v145 offset:576
	v_add_u32_e32 v147, 0x90, v146
	s_waitcnt lgkmcnt(0)
; __device__ __forceinline__ unsigned pk2(float lo, float hi) { unsigned r; asm volatile("v_cvt_pk_bf16_f32 %0, %1, %2" : "=v"(r) : "v"(lo), "v"(hi)); return r; }
; __device__ __forceinline__ float siluf_(float x) { return x * __builtin_amdgcn_rcpf(1.0f + __expf(-x)); }
;     template <int mode> __device__ __forceinline__ void run(const f32x4 (&acc)[2][2][4][2], const Unit& u, int wr, int wc, int fr, int fq, const LAS float* sc) const {
;     ...
;                     const int row = row0 + ai * HALF + m * 16;
;                     const float s = sc[ai * HALF + wr * 64 + m * 16 + fr];
;                     const f32x4 g0 = acc[ai][0][m][0] * s, u0 = acc[ai][1][m][0] * s, g1 = acc[ai][0][m][1] * s, u1 = acc[ai][1][m][1] * s;
;                     u32x4 w;
;                     w.x = pk2(siluf_(g0[0]) * u0[0], siluf_(g0[1]) * u0[1]); w.y = pk2(siluf_(g0[2]) * u0[2], siluf_(g0[3]) * u0[3]);
;                     w.z = pk2(siluf_(g1[0]) * u1[0], siluf_(g1[1]) * u1[1]); w.w = pk2(siluf_(g1[2]) * u1[2], siluf_(g1[3]) * u1[3]);
;                     *(u32x4*)(ob + (size_t)row * FF + col0) = w;
	v_pk_mul_f32 v[152:153], v[54:55], v[148:149] op_sel_hi:[1,0]
	v_pk_mul_f32 v[150:151], v[56:57], v[148:149] op_sel_hi:[1,0]
	v_pk_mul_f32 v[154:155], v[24:25], v[148:149] op_sel_hi:[1,0]
	v_pk_mul_f32 v[156:157], v[22:23], v[148:149] op_sel_hi:[1,0]
	v_pk_mul_f32 v[158:159], v[52:53], v[148:149] op_sel_hi:[1,0]
	v_pk_mul_f32 v[160:161], v[50:51], v[148:149] op_sel_hi:[1,0]
	v_pk_mul_f32 v[162:163], v[20:21], v[148:149] op_sel_hi:[1,0]
	v_pk_mul_f32 v[164:165], v[18:19], v[148:149] op_sel_hi:[1,0]
	v_mul_f32_e32 v148, 0xbfb8aa3b, v152
	v_mul_f32_e32 v149, 0xbfb8aa3b, v153
	v_exp_f32_e32 v148, v148
	v_exp_f32_e32 v149, v149
	v_add_f32_e32 v148, 1.0, v148
	v_add_f32_e32 v149, 1.0, v149
	v_rcp_f32_e32 v148, v148
	v_rcp_f32_e32 v149, v149
	v_mul_f32_e32 v148, v152, v148
	v_mul_f32_e32 v149, v153, v149
	v_mul_f32_e32 v148, v156, v148
	v_mul_f32_e32 v149, v157, v149
	v_cvt_pk_bf16_f32 v148, v148, v149
	v_mul_f32_e32 v149, 0xbfb8aa3b, v150
	v_exp_f32_e32 v149, v149
	v_mul_f32_e32 v152, 0xbfb8aa3b, v159
	v_exp_f32_e32 v152, v152
	v_add_f32_e32 v149, 1.0, v149
	v_rcp_f32_e32 v149, v149
	v_add_f32_e32 v152, 1.0, v152
	v_rcp_f32_e32 v152, v152
	v_mul_f32_e32 v149, v150, v149
	v_mul_f32_e32 v150, 0xbfb8aa3b, v151
	v_exp_f32_e32 v150, v150
	v_mul_f32_e32 v149, v154, v149
	v_mul_f32_e32 v152, v159, v152
	v_mul_f32_e32 v152, v163, v152
	v_add_f32_e32 v150, 1.0, v150
	v_rcp_f32_e32 v150, v150
	s_nop 0
	v_mul_f32_e32 v150, v151, v150
	v_mul_f32_e32 v150, v155, v150
	v_cvt_pk_bf16_f32 v149, v149, v150
	v_mul_f32_e32 v150, 0xbfb8aa3b, v160
	v_mul_f32_e32 v151, 0xbfb8aa3b, v161
	v_exp_f32_e32 v150, v150
	v_exp_f32_e32 v151, v151
	v_add_f32_e32 v150, 1.0, v150
	v_add_f32_e32 v151, 1.0, v151
	v_rcp_f32_e32 v150, v150
	v_rcp_f32_e32 v151, v151
	v_mul_f32_e32 v150, v160, v150
	v_mul_f32_e32 v151, v161, v151
	v_mul_f32_e32 v150, v164, v150
	v_mul_f32_e32 v151, v165, v151
	v_cvt_pk_bf16_f32 v150, v150, v151
	v_mul_f32_e32 v151, 0xbfb8aa3b, v158
	v_exp_f32_e32 v151, v151
	s_nop 0
	v_add_f32_e32 v151, 1.0, v151
	v_rcp_f32_e32 v151, v151
	s_nop 0
	v_mul_f32_e32 v151, v158, v151
	v_mul_f32_e32 v151, v162, v151
	v_cvt_pk_bf16_f32 v151, v151, v152
	v_mad_i64_i32 v[152:153], s[4:5], v147, s33, v[136:137]
	v_lshl_add_u64 v[152:153], v[152:153], 0, v[138:139]
	global_store_dwordx4 v[152:153], v[148:151], off
	ds_read_b32 v148, v145 offset:640
	v_add_u32_e32 v147, 0xa0, v146
	s_waitcnt lgkmcnt(0)
	v_pk_mul_f32 v[152:153], v[46:47], v[148:149] op_sel_hi:[1,0]
	v_pk_mul_f32 v[150:151], v[48:49], v[148:149] op_sel_hi:[1,0]
	v_pk_mul_f32 v[154:155], v[16:17], v[148:149] op_sel_hi:[1,0]
	v_pk_mul_f32 v[156:157], v[14:15], v[148:149] op_sel_hi:[1,0]
	v_pk_mul_f32 v[158:159], v[44:45], v[148:149] op_sel_hi:[1,0]
	v_pk_mul_f32 v[160:161], v[42:43], v[148:149] op_sel_hi:[1,0]
	v_pk_mul_f32 v[162:163], v[12:13], v[148:149] op_sel_hi:[1,0]
	v_pk_mul_f32 v[164:165], v[10:11], v[148:149] op_sel_hi:[1,0]
	v_mul_f32_e32 v148, 0xbfb8aa3b, v152
	v_mul_f32_e32 v149, 0xbfb8aa3b, v153
	v_exp_f32_e32 v148, v148
	v_exp_f32_e32 v149, v149
	v_add_f32_e32 v148, 1.0, v148
	v_add_f32_e32 v149, 1.0, v149
	v_rcp_f32_e32 v148, v148
	v_rcp_f32_e32 v149, v149
	v_mul_f32_e32 v148, v152, v148
	v_mul_f32_e32 v149, v153, v149
	v_mul_f32_e32 v148, v156, v148
	v_mul_f32_e32 v149, v157, v149
	v_cvt_pk_bf16_f32 v148, v148, v149
	v_mul_f32_e32 v149, 0xbfb8aa3b, v150
	v_exp_f32_e32 v149, v149
	v_mul_f32_e32 v152, 0xbfb8aa3b, v159
	v_exp_f32_e32 v152, v152
	v_add_f32_e32 v149, 1.0, v149
	v_rcp_f32_e32 v149, v149
	v_add_f32_e32 v152, 1.0, v152
	v_rcp_f32_e32 v152, v152
	v_mul_f32_e32 v149, v150, v149
	v_mul_f32_e32 v150, 0xbfb8aa3b, v151
	v_exp_f32_e32 v150, v150
	v_mul_f32_e32 v149, v154, v149
	v_mul_f32_e32 v152, v159, v152
	v_mul_f32_e32 v152, v163, v152
	v_add_f32_e32 v150, 1.0, v150
	v_rcp_f32_e32 v150, v150
	s_nop 0
	v_mul_f32_e32 v150, v151, v150
	v_mul_f32_e32 v150, v155, v150
	v_cvt_pk_bf16_f32 v149, v149, v150
	v_mul_f32_e32 v150, 0xbfb8aa3b, v160
	v_mul_f32_e32 v151, 0xbfb8aa3b, v161
	v_exp_f32_e32 v150, v150
	v_exp_f32_e32 v151, v151
	v_add_f32_e32 v150, 1.0, v150
	v_add_f32_e32 v151, 1.0, v151
	v_rcp_f32_e32 v150, v150
	v_rcp_f32_e32 v151, v151
	v_mul_f32_e32 v150, v160, v150
	v_mul_f32_e32 v151, v161, v151
	v_mul_f32_e32 v150, v164, v150
	v_mul_f32_e32 v151, v165, v151
	v_cvt_pk_bf16_f32 v150, v150, v151
	v_mul_f32_e32 v151, 0xbfb8aa3b, v158
	v_exp_f32_e32 v151, v151
	v_add_u32_e32 v164, 0xb0, v146
	v_add_f32_e32 v151, 1.0, v151
	v_rcp_f32_e32 v151, v151
	s_nop 0
	v_mul_f32_e32 v151, v158, v151
	v_mul_f32_e32 v151, v162, v151
	v_cvt_pk_bf16_f32 v151, v151, v152
	ds_read_b32 v146, v145 offset:704
	v_mad_i64_i32 v[152:153], s[4:5], v147, s33, v[136:137]
	v_lshl_add_u64 v[152:153], v[152:153], 0, v[138:139]
	global_store_dwordx4 v[152:153], v[148:151], off
	s_waitcnt lgkmcnt(0)
; __device__ __forceinline__ unsigned pk2(float lo, float hi) { unsigned r; asm volatile("v_cvt_pk_bf16_f32 %0, %1, %2" : "=v"(r) : "v"(lo), "v"(hi)); return r; }
; __device__ __forceinline__ float siluf_(float x) { return x * __builtin_amdgcn_rcpf(1.0f + __expf(-x)); }
;     template <int mode> __device__ __forceinline__ void run(const f32x4 (&acc)[2][2][4][2], const Unit& u, int wr, int wc, int fr, int fq, const LAS float* sc) const {
;     ...
;                     const int row = row0 + ai * HALF + m * 16;
;                     const float s = sc[ai * HALF + wr * 64 + m * 16 + fr];
;                     const f32x4 g0 = acc[ai][0][m][0] * s, u0 = acc[ai][1][m][0] * s, g1 = acc[ai][0][m][1] * s, u1 = acc[ai][1][m][1] * s;
;                     u32x4 w;
;                     w.x = pk2(siluf_(g0[0]) * u0[0], siluf_(g0[1]) * u0[1]); w.y = pk2(siluf_(g0[2]) * u0[2], siluf_(g0[3]) * u0[3]);
;                     w.z = pk2(siluf_(g1[0]) * u1[0], siluf_(g1[1]) * u1[1]); w.w = pk2(siluf_(g1[2]) * u1[2], siluf_(g1[3]) * u1[3]);
;                     *(u32x4*)(ob + (size_t)row * FF + col0) = w;
; template <int MODE, class EpiT, class Sched>
; __device__ __forceinline__ void gemm_phase(LAS unsigned char* lds, const Gemm g, const Sched& S, const EpiT& E) {
;     ...
;         if (!has_next) break;
; #pragma unroll
;         for (int a = 0; a < 2; ++a)
; #pragma unroll
;             for (int b = 0; b < 2; ++b)
; #pragma unroll
;                 for (int m = 0; m < 4; ++m)
; #pragma unroll
;                     for (int n = 0; n < 2; ++n) acc[a][b][m][n] = (f32x4){0.f, 0.f, 0.f, 0.f};
;         cur = nxt; cA = nA; cB = nB; ++ui;
	v_pk_mul_f32 v[152:153], v[8:9], v[146:147] op_sel_hi:[1,0]
	v_pk_mul_f32 v[154:155], v[6:7], v[146:147] op_sel_hi:[1,0]
	v_pk_mul_f32 v[150:151], v[38:39], v[146:147] op_sel_hi:[1,0]
	v_pk_mul_f32 v[148:149], v[40:41], v[146:147] op_sel_hi:[1,0]
	v_pk_mul_f32 v[156:157], v[36:37], v[146:147] op_sel_hi:[1,0]
	v_pk_mul_f32 v[158:159], v[34:35], v[146:147] op_sel_hi:[1,0]
	v_pk_mul_f32 v[160:161], v[4:5], v[146:147] op_sel_hi:[1,0]
	v_pk_mul_f32 v[162:163], v[2:3], v[146:147] op_sel_hi:[1,0]
	v_mul_f32_e32 v145, 0xbfb8aa3b, v150
	v_mul_f32_e32 v146, 0xbfb8aa3b, v151
	v_exp_f32_e32 v145, v145
	v_exp_f32_e32 v146, v146
	v_mul_f32_e32 v147, 0xbfb8aa3b, v149
	v_exp_f32_e32 v147, v147
	v_add_f32_e32 v145, 1.0, v145
	v_add_f32_e32 v146, 1.0, v146
	v_rcp_f32_e32 v145, v145
	v_rcp_f32_e32 v146, v146
	v_add_f32_e32 v147, 1.0, v147
	v_rcp_f32_e32 v147, v147
	v_mul_f32_e32 v145, v150, v145
	v_mul_f32_e32 v146, v151, v146
	v_mul_f32_e32 v145, v154, v145
	v_mul_f32_e32 v146, v155, v146
	v_cvt_pk_bf16_f32 v146, v145, v146
	v_mul_f32_e32 v145, 0xbfb8aa3b, v148
	v_exp_f32_e32 v145, v145
	v_mul_f32_e32 v147, v149, v147
	v_mul_f32_e32 v147, v153, v147
	v_mul_f32_e32 v149, 0xbfb8aa3b, v157
	v_add_f32_e32 v145, 1.0, v145
	v_rcp_f32_e32 v145, v145
	v_exp_f32_e32 v149, v149
	v_mad_i64_i32 v[136:137], s[4:5], v164, s33, v[136:137]
	v_mul_f32_e32 v145, v148, v145
	v_mul_f32_e32 v145, v152, v145
	v_cvt_pk_bf16_f32 v147, v145, v147
	v_mul_f32_e32 v145, 0xbfb8aa3b, v158
	v_mul_f32_e32 v148, 0xbfb8aa3b, v159
	v_exp_f32_e32 v145, v145
	v_exp_f32_e32 v148, v148
	v_add_f32_e32 v149, 1.0, v149
	v_rcp_f32_e32 v149, v149
	v_add_f32_e32 v145, 1.0, v145
	v_add_f32_e32 v148, 1.0, v148
	v_rcp_f32_e32 v145, v145
	v_rcp_f32_e32 v148, v148
	v_mul_f32_e32 v149, v157, v149
	v_mul_f32_e32 v149, v161, v149
	v_mul_f32_e32 v145, v158, v145
	v_mul_f32_e32 v148, v159, v148
	v_mul_f32_e32 v145, v162, v145
	v_mul_f32_e32 v148, v163, v148
	v_cvt_pk_bf16_f32 v148, v145, v148
	v_mul_f32_e32 v145, 0xbfb8aa3b, v156
	v_exp_f32_e32 v145, v145
	v_lshl_add_u64 v[136:137], v[136:137], 0, v[138:139]
	v_add_f32_e32 v145, 1.0, v145
	v_rcp_f32_e32 v145, v145
	s_nop 0
	v_mul_f32_e32 v145, v156, v145
	v_mul_f32_e32 v145, v160, v145
	v_cvt_pk_bf16_f32 v149, v145, v149
	global_store_dwordx4 v[136:137], v[146:149], off
	s_cbranch_vccnz .LBB0_324
	v_mov_b32_e32 v2, 0
	s_mov_b32 s9, s61
	s_mov_b32 s8, s60
	s_mov_b64 s[12:13], s[28:29]
	s_mov_b64 s[10:11], s[34:35]
	s_mov_b32 s57, s2
	v_mov_b32_e32 v3, v2
	v_mov_b32_e32 v4, v2
	v_mov_b32_e32 v5, v2
	v_mov_b32_e32 v6, v2
	v_mov_b32_e32 v7, v2
	v_mov_b32_e32 v8, v2
	v_mov_b32_e32 v9, v2
	v_mov_b32_e32 v10, v2
	v_mov_b32_e32 v11, v2
	v_mov_b32_e32 v12, v2
	v_mov_b32_e32 v13, v2
	v_mov_b32_e32 v14, v2
	v_mov_b32_e32 v15, v2
	v_mov_b32_e32 v16, v2
	v_mov_b32_e32 v17, v2
	v_mov_b32_e32 v18, v2
	v_mov_b32_e32 v19, v2
	v_mov_b32_e32 v20, v2
	v_mov_b32_e32 v21, v2
	v_mov_b32_e32 v22, v2
	v_mov_b32_e32 v23, v2
	v_mov_b32_e32 v24, v2
	v_mov_b32_e32 v25, v2
	v_mov_b32_e32 v26, v2
	v_mov_b32_e32 v27, v2
	v_mov_b32_e32 v28, v2
	v_mov_b32_e32 v29, v2
	v_mov_b32_e32 v30, v2
	v_mov_b32_e32 v31, v2
	v_mov_b32_e32 v32, v2
	v_mov_b32_e32 v33, v2
	v_mov_b32_e32 v34, v2
	v_mov_b32_e32 v35, v2
	v_mov_b32_e32 v36, v2
	v_mov_b32_e32 v37, v2
	v_mov_b32_e32 v38, v2
	v_mov_b32_e32 v39, v2
	v_mov_b32_e32 v40, v2
	v_mov_b32_e32 v41, v2
	v_mov_b32_e32 v42, v2
	v_mov_b32_e32 v43, v2
	v_mov_b32_e32 v44, v2
	v_mov_b32_e32 v45, v2
	v_mov_b32_e32 v46, v2
	v_mov_b32_e32 v47, v2
	v_mov_b32_e32 v48, v2
	v_mov_b32_e32 v49, v2
	v_mov_b32_e32 v50, v2
	v_mov_b32_e32 v51, v2
	v_mov_b32_e32 v52, v2
	v_mov_b32_e32 v53, v2
	v_mov_b32_e32 v54, v2
	v_mov_b32_e32 v55, v2
	v_mov_b32_e32 v56, v2
	v_mov_b32_e32 v57, v2
	v_mov_b32_e32 v58, v2
	v_mov_b32_e32 v59, v2
	v_mov_b32_e32 v60, v2
	v_mov_b32_e32 v61, v2
	v_mov_b32_e32 v62, v2
	v_mov_b32_e32 v63, v2
	v_mov_b32_e32 v64, v2
	v_mov_b32_e32 v65, v2
	v_mov_b32_e32 v66, v2
	v_mov_b32_e32 v67, v2
	v_mov_b32_e32 v68, v2
	v_mov_b32_e32 v69, v2
	v_mov_b32_e32 v70, v2
	v_mov_b32_e32 v71, v2
	v_mov_b32_e32 v72, v2
	v_mov_b32_e32 v73, v2
	v_mov_b32_e32 v74, v2
	v_mov_b32_e32 v75, v2
	v_mov_b32_e32 v76, v2
	v_mov_b32_e32 v77, v2
	v_mov_b32_e32 v78, v2
	v_mov_b32_e32 v79, v2
	v_mov_b32_e32 v80, v2
	v_mov_b32_e32 v81, v2
	v_mov_b32_e32 v82, v2
	v_mov_b32_e32 v83, v2
	v_mov_b32_e32 v84, v2
	v_mov_b32_e32 v85, v2
	v_mov_b32_e32 v86, v2
	v_mov_b32_e32 v87, v2
	v_mov_b32_e32 v88, v2
	v_mov_b32_e32 v89, v2
	v_mov_b32_e32 v90, v2
	v_mov_b32_e32 v91, v2
	v_mov_b32_e32 v92, v2
	v_mov_b32_e32 v93, v2
	v_mov_b32_e32 v94, v2
	v_mov_b32_e32 v95, v2
	v_mov_b32_e32 v96, v2
	v_mov_b32_e32 v97, v2
	v_mov_b32_e32 v98, v2
	v_mov_b32_e32 v99, v2
	v_mov_b32_e32 v100, v2
	v_mov_b32_e32 v101, v2
	v_mov_b32_e32 v102, v2
	v_mov_b32_e32 v103, v2
	v_mov_b32_e32 v104, v2
	v_mov_b32_e32 v105, v2
	v_mov_b32_e32 v106, v2
	v_mov_b32_e32 v107, v2
	v_mov_b32_e32 v108, v2
	v_mov_b32_e32 v109, v2
	v_mov_b32_e32 v110, v2
	v_mov_b32_e32 v111, v2
	v_mov_b32_e32 v112, v2
	v_mov_b32_e32 v113, v2
	v_mov_b32_e32 v114, v2
	v_mov_b32_e32 v115, v2
	v_mov_b32_e32 v116, v2
	v_mov_b32_e32 v117, v2
	v_mov_b32_e32 v118, v2
	v_mov_b32_e32 v119, v2
	v_mov_b32_e32 v120, v2
	v_mov_b32_e32 v121, v2
	v_mov_b32_e32 v122, v2
	v_mov_b32_e32 v123, v2
	v_mov_b32_e32 v124, v2
	v_mov_b32_e32 v125, v2
	v_mov_b32_e32 v126, v2
	v_mov_b32_e32 v127, v2
	v_mov_b32_e32 v128, v2
	v_mov_b32_e32 v129, v2
	s_branch .LBB0_324

; __global__ void __launch_bounds__(NTHREADS, 2) mk_fwd(Params P_arg) {
	.amdhsa_kernel _Z6mk_fwd6Params
		.amdhsa_group_segment_fixed_size 0
		.amdhsa_private_segment_fixed_size 0
		.amdhsa_kernarg_size 544
		.amdhsa_user_sgpr_count 2
		.amdhsa_user_sgpr_dispatch_ptr 0
		.amdhsa_user_sgpr_queue_ptr 0
		.amdhsa_user_sgpr_kernarg_segment_ptr 1
		.amdhsa_user_sgpr_dispatch_id 0
		.amdhsa_user_sgpr_kernarg_preload_length 0
		.amdhsa_user_sgpr_kernarg_preload_offset 0
		.amdhsa_user_sgpr_private_segment_size 0
		.amdhsa_uses_dynamic_stack 0
		.amdhsa_enable_private_segment 0
		.amdhsa_system_sgpr_workgroup_id_x 1
		.amdhsa_system_sgpr_workgroup_id_y 0
		.amdhsa_system_sgpr_workgroup_id_z 0
		.amdhsa_system_sgpr_workgroup_info 0
		.amdhsa_system_vgpr_workitem_id 2
		.amdhsa_next_free_vgpr 249
		.amdhsa_next_free_sgpr 102
		.amdhsa_accum_offset 252
		.amdhsa_reserve_vcc 1
		.amdhsa_float_round_mode_32 0
		.amdhsa_float_round_mode_16_64 0
		.amdhsa_float_denorm_mode_32 3
		.amdhsa_float_denorm_mode_16_64 3
		.amdhsa_dx10_clamp 1
		.amdhsa_ieee_mode 1
		.amdhsa_fp16_overflow 0
		.amdhsa_tg_split 0
		.amdhsa_exception_fp_ieee_invalid_op 0
		.amdhsa_exception_fp_denorm_src 0
		.amdhsa_exception_fp_ieee_div_zero 0
		.amdhsa_exception_fp_ieee_overflow 0
		.amdhsa_exception_fp_ieee_underflow 0
		.amdhsa_exception_fp_ieee_inexact 0
		.amdhsa_exception_int_div_zero 0
	.end_amdhsa_kernel

; __global__ void __launch_bounds__(NTHREADS, 2) mk_fwd(Params P_arg) {
amdhsa.kernels:
  - .agpr_count:     0
    .args:
      - .offset:         0
        .size:           288
        .value_kind:     by_value
      - .offset:         288
        .size:           4
        .value_kind:     hidden_block_count_x
      - .offset:         292
        .size:           4
        .value_kind:     hidden_block_count_y
      - .offset:         296
        .size:           4
        .value_kind:     hidden_block_count_z
      - .offset:         300
        .size:           2
        .value_kind:     hidden_group_size_x
      - .offset:         302
        .size:           2
        .value_kind:     hidden_group_size_y
      - .offset:         304
        .size:           2
        .value_kind:     hidden_group_size_z
      - .offset:         306
        .size:           2
        .value_kind:     hidden_remainder_x
      - .offset:         308
        .size:           2
        .value_kind:     hidden_remainder_y
      - .offset:         310
        .size:           2
        .value_kind:     hidden_remainder_z
      - .offset:         328
        .size:           8
        .value_kind:     hidden_global_offset_x
      - .offset:         336
        .size:           8
        .value_kind:     hidden_global_offset_y
      - .offset:         344
        .size:           8
        .value_kind:     hidden_global_offset_z
      - .offset:         352
        .size:           2
        .value_kind:     hidden_grid_dims
      - .offset:         376
        .size:           8
        .value_kind:     hidden_multigrid_sync_arg
      - .offset:         408
        .size:           4
        .value_kind:     hidden_dynamic_lds_size
    .group_segment_fixed_size: 0
    .kernarg_segment_align: 8
    .kernarg_segment_size: 544
    .language:       OpenCL C
    .language_version:
      - 2
      - 0
    .max_flat_workgroup_size: 512
    .name:           _Z6mk_fwd6Params
    .private_segment_fixed_size: 0
    .sgpr_count:     108
    .sgpr_spill_count: 174
    .symbol:         _Z6mk_fwd6Params.kd
    .uniform_work_group_size: 1
    .uses_dynamic_stack: false
    .vgpr_count:     249
    .vgpr_spill_count: 0
    .wavefront_size: 64
